# adds E24: band attention unit order rotated per round so the cheaper 4-tile units are spread evenly over CUs (load balance), stacked on E23
# speedup vs baseline: 1.0045x; 1.0045x over previous
.LBB0_526:
	s_bfe_u32 s21, s86, 0x10008
	s_lshl_b32 s5, s21, 1
	s_lshr_b32 s6, 0x1000, s5
	s_lshl_b32 s7, s86, 8
	s_and_b32 s7, s7, 0xf00
	s_add_i32 s6, s6, -1
	s_sub_i32 s5, 12, s5
	s_and_b32 s76, s6, s7
	s_xor_b64 s[2:3], s[2:3], -1
	s_bfe_i32 s13, s86, 0x10008
	s_ashr_i32 s4, s86, 9
	s_bfe_u32 s23, s86, 0x40004
	s_lshr_b32 s14, s7, s5
	s_add_i32 s5, s76, 0xffffff80
	s_cmp_eq_u32 s76, 0
	s_cselect_b32 s10, 0, s5
	s_mul_i32 s5, s4, 3
	s_cselect_b32 s88, 4, 6
	s_cselect_b32 s20, 0, 0x80
	s_add_i32 s5, s5, s21
	s_mul_i32 s6, s5, 3
	s_ashr_i32 s7, s6, 31
	s_lshl_b64 s[6:7], s[6:7], 23
	s_add_u32 s5, s94, s6
	s_addc_u32 s6, s95, s7
	s_lshl_b32 s7, s23, 19
	s_add_u32 s5, s5, s7
	s_addc_u32 s6, s6, 0
	s_lshl_b32 s7, s14, 7
	s_add_u32 s5, s5, s7
	s_addc_u32 s15, s6, 0
	s_cmp_eq_u32 s21, 0
	s_cselect_b64 s[8:9], -1, 0
	s_and_b64 s[6:7], s[8:9], exec
	s_cselect_b32 s83, 6, 8
	s_cselect_b32 s22, 64, 0x100
	s_lshl_b64 s[6:7], s[76:77], s83
	s_lshl_b64 s[6:7], s[6:7], 1
	s_add_u32 s6, s5, s6
	s_addc_u32 s7, s15, s7
	s_ashr_i32 s11, s10, 31
	s_lshl_b64 s[10:11], s[10:11], s83
	s_lshl_b64 s[10:11], s[10:11], 1
	s_add_u32 s5, s5, s10
	s_addc_u32 s10, s15, s11
	s_add_u32 s26, s5, 0x800000
	s_addc_u32 s27, s10, 0
	s_add_u32 s18, s5, 0x1000000
	s_addc_u32 s19, s10, 0
	s_ashr_i32 s5, s4, 31
	s_lshl_b64 s[4:5], s[4:5], 12
	s_and_b32 s10, s13, 2
	s_or_b32 s4, s4, s14
	s_lshl_b64 s[10:11], s[76:77], s10
	s_add_u32 s4, s4, s10
	s_mov_b32 s12, s86
	s_addc_u32 s5, s5, s11
	s_cmp_eq_u32 s84, 0x100
	s_cbranch_scc0 .Lrb_plain
	s_bfe_u32 s10, s86, 0x10008
	s_add_i32 s10, s10, 1
	s_and_b32 s11, s86, 0xff
	s_add_i32 s11, s11, s10
	s_and_b32 s11, s11, 0xff
	s_andn2_b32 s86, s86, 0xff
	s_addk_i32 s86, 0x100
	s_or_b32 s86, s86, s11
	s_branch .Lrb_done
.Lrb_plain:
	s_add_i32 s86, s86, s84
.Lrb_done:
	s_cmpk_lt_i32 s86, 0x1000
	s_cselect_b64 s[14:15], -1, 0
	s_cmpk_gt_i32 s86, 0xfff
	s_cselect_b64 s[10:11], -1, 0
	v_writelane_b32 v254, s10, 54
	v_cndmask_b32_e64 v0, 0, 1, s[2:3]
	s_mov_b64 s[0:1], -1
	v_writelane_b32 v254, s11, 55
	s_and_b64 s[10:11], s[14:15], exec
	s_cselect_b32 s28, s86, s12
	s_bfe_u32 s16, s28, 0x10008
	s_cmp_eq_u32 s16, 0
	s_cselect_b64 s[12:13], -1, 0
	s_and_b64 s[10:11], s[12:13], exec
	s_cselect_b32 s89, 64, 0x100
	s_lshl_b32 s10, s16, 1
	s_lshr_b32 s17, 0x1000, s10
	s_lshl_b32 s29, s28, 8
	s_and_b32 s29, s29, 0xf00
	s_add_i32 s17, s17, -1
	s_sub_i32 s10, 12, s10
	s_and_b32 s76, s17, s29
	s_ashr_i32 s11, s28, 9
	s_lshr_b32 s33, s29, s10
	s_add_i32 s10, s76, 0xffffff80
	s_cmp_lg_u32 s76, 0
	s_mul_i32 s11, s11, 3
	s_cselect_b32 s10, s10, 0
	s_add_i32 s11, s11, s16
	s_mul_i32 s16, s11, 3
	s_ashr_i32 s17, s16, 31
	s_lshl_b64 s[16:17], s[16:17], 23
	s_add_u32 s11, s94, s16
	s_addc_u32 s16, s95, s17
	s_lshl_b32 s17, s28, 15
	s_and_b32 s17, s17, 0x780000
	s_add_u32 s11, s11, s17
	s_addc_u32 s16, s16, 0
	s_lshl_b32 s17, s33, 7
	s_add_u32 s28, s11, s17
	s_addc_u32 s29, s16, 0
	s_and_b64 s[16:17], s[12:13], exec
	s_cselect_b32 s92, 6, 8
	s_lshl_b64 s[16:17], s[76:77], s92
	s_lshl_b64 s[16:17], s[16:17], 1
	s_add_u32 s16, s28, s16
	s_addc_u32 s17, s29, s17
	s_ashr_i32 s11, s10, 31
	s_lshl_b64 s[10:11], s[10:11], s92
	s_lshl_b64 s[10:11], s[10:11], 1
	s_add_u32 s10, s28, s10
	s_addc_u32 s11, s29, s11
	s_add_u32 s28, s10, 0x800000
	s_addc_u32 s29, s11, 0
	s_lshl_b32 s10, s21, 21
	v_readlane_b32 s11, v251, 16
	s_add_u32 s10, s11, s10
	v_readlane_b32 s11, v251, 17
	s_addc_u32 s11, s11, 0
	s_lshl_b64 s[4:5], s[4:5], 6
	s_add_u32 s4, s10, s4
	s_addc_u32 s5, s11, s5
	s_lshl_b32 s10, s23, 2
	s_add_u32 s10, s4, s10
	s_addc_u32 s11, s5, 0
	s_and_b64 s[4:5], s[14:15], exec
	v_readlane_b32 s4, v254, 52
	v_readlane_b32 s5, v254, 53
	s_cselect_b32 s15, s17, 0
	s_cselect_b32 s14, s16, 0
	s_cselect_b32 s17, s29, 0
	s_cselect_b32 s16, s28, 0
	s_and_b64 vcc, exec, s[4:5]
	v_cmp_ne_u32_e64 s[38:39], 1, v0
	s_cbranch_vccz .LBB0_620
	v_mov_b32_e32 v32, v230
	v_mov_b32_e32 v3, v193
	v_readfirstlane_b32 s4, v32
	v_and_b32_e32 v192, 63, v32
	s_ashr_i32 s2, s4, 6
	v_lshlrev_b64 v[0:1], s83, v[192:193]
	s_lshl_b32 s74, s2, 3
	v_lshl_add_u64 v[0:1], v[0:1], 1, s[26:27]
	s_ashr_i32 s75, s74, 31
	v_lshl_add_u64 v[206:207], s[74:75], 1, v[0:1]
	s_lshl_b32 s0, s2, 4
	v_bfe_u32 v0, v32, 2, 4
	v_and_or_b32 v0, s0, 48, v0
	s_ashr_i32 s0, s4, 3
	v_mov_b32_e32 v1, v193
	s_andn2_b32 s0, s0, 31
	s_lshl_b32 s78, s2, 5
	v_lshlrev_b64 v[0:1], s83, v[0:1]
	s_ashr_i32 s1, s0, 31
	v_lshlrev_b32_e32 v189, 3, v32
	s_lshl_b32 s79, s2, 10
	v_lshl_add_u64 v[0:1], v[0:1], 1, s[18:19]
	v_and_b32_e32 v191, 24, v189
	s_cmp_lg_u32 0, -1
	v_lshl_add_u64 v[0:1], s[0:1], 1, v[0:1]
	v_lshlrev_b32_e32 v2, 1, v191
	s_cselect_b32 s0, 0, 0
	v_lshl_add_u64 v[208:209], v[0:1], 0, v[2:3]
	s_add_i32 s90, s79, s0
	v_and_b32_e32 v0, 56, v189
	s_add_i32 s94, s90, 0x6000
	s_mov_b64 s[0:1], -1
	s_and_b64 vcc, exec, s[38:39]
	v_lshrrev_b32_e32 v188, 3, v192
	v_lshlrev_b32_e32 v204, 1, v0
	s_cbranch_vccz .LBB0_607
	s_andn2_b64 vcc, exec, s[0:1]
	s_cbranch_vccz .LBB0_608
